# attn_c back-edge rotation: latch SALU and next-tile test moved in front of the tile barrier
# speedup vs baseline: 1.0029x; 1.0029x over previous
; DI void phase_attn_c(const Params& P, int l, char* shm, int dry) {
;     ...
;   for (int it = blockIdx.x; it < 256; it += gridDim.x) {
;     const int bh = it >> 4, pr = it & 15, b = bh >> 2, h = bh & 3;
; #pragma clang loop unroll(disable)
;     for (int hf = 0; hf < 2; ++hf) attn_c_item(P, l, b, h, hf ? pr : 31 - pr, shm, B2, dry);
.LBB0_575:
	s_nop 0
	v_readfirstlane_b32 s98, v135
	s_nop 0
	s_cmp_lt_u32 s98, 0x100
	s_cbranch_scc1 .Lsp_skipc
	s_setprio 1

; DI void attn_c_item(const Params& P, int l, int b, int h, int qb, char* shm, float B2, int dry) {
;     ...
;   for (int kt = 0; kt < ntile; ++kt) {
;     const int cur = kt & 1;
;     if (kt + 1 < ntile) A_STAGE(cur ^ 1, kt + 1);
.LBB0_576:
	s_cmp_lg_u32 s98, 0
	s_cbranch_scc1 .LBB0_578

; DI float bflo(unsigned v) { return __uint_as_float(v << 16); }
; DI float bfhi(unsigned v) { return __uint_as_float(v & 0xffff0000u); }
; DI void attn_c_item(const Params& P, int l, int b, int h, int qb, char* shm, float B2, int dry) {
;     ...
;     asm volatile("s_waitcnt vmcnt(0)" ::: "memory");
;     __syncthreads();
;   }
;     ...
;   u16* actC = (u16*)(P.ws + OFF_ACTC);
; #pragma unroll
;   for (int qs = 0; qs < 2; ++qs) {
;     float lt = lsum[qs];
;     lt += __shfl_xor(lt, 16);
;     lt += __shfl_xor(lt, 32);
;     const float inv = 1.f / lt;
;     u16* dp = actC + (size_t)(b * SEQ + q0 + qs * 16 + fr) * 512 + h * 128 + fq * 4;
; #pragma unroll
;     for (int dvs = 0; dvs < 8; ++dvs) {
;       u32x2 gz = *(const u32x2*)(dp + dvs * 16);
;       u32x2 ov = {pack2(o[dvs][qs][0] * inv * bflo(gz[0]), o[dvs][qs][1] * inv * bfhi(gz[0])),
;                   pack2(o[dvs][qs][2] * inv * bflo(gz[1]), o[dvs][qs][3] * inv * bfhi(gz[1]))};
;       if (!dry) *(u32x2*)(dp + dvs * 16) = ov;
;     }
;   }
.LBB0_580:
	s_waitcnt vmcnt(0)
	v_add_u32_e32 v122, 0x3000, v122
	v_add_u32_e32 v123, 0x3000, v123
	v_add_u32_e32 v124, 0x3000, v124
	v_add_u32_e32 v125, 64, v125
	s_cmp_lg_u32 s0, s35
	s_cselect_b32 s99, 1, 0
	v_add_u32_e32 v126, 64, v126
	s_mov_b32 s36, s35
	s_and_b32 s37, s36, 1
	s_add_i32 s35, s36, 1
	s_cmp_ge_u32 s35, s0
	s_cselect_b32 s98, 1, 0
	s_waitcnt vmcnt(0) lgkmcnt(0)
	s_barrier
	s_cmp_lg_u32 s99, 0
	s_cbranch_scc1 .LBB0_576
	ds_bpermute_b32 v32, v212, v119
	v_lshlrev_b32_e32 v132, 1, v116
	v_lshl_add_u64 v[34:35], s[18:19], 0, v[132:133]
	s_waitcnt lgkmcnt(0)
	v_add_f32_e32 v32, v119, v32
	ds_bpermute_b32 v33, v211, v32
	s_waitcnt lgkmcnt(0)
	v_add_f32_e32 v32, v32, v33
	v_div_scale_f32 v33, s[0:1], v32, v32, 1.0
	v_rcp_f32_e32 v36, v33
	s_nop 0
	v_fma_f32 v37, -v33, v36, 1.0
	v_fmac_f32_e32 v36, v37, v36
	v_div_scale_f32 v37, vcc, 1.0, v32, 1.0
	v_mul_f32_e32 v38, v37, v36
	v_fma_f32 v39, -v33, v38, v37
	v_fmac_f32_e32 v38, v39, v36
	v_fma_f32 v33, -v33, v38, v37
	v_div_fmas_f32 v33, v33, v36, v38
	v_lshlrev_b64 v[36:37], 10, v[114:115]
	v_lshl_add_u64 v[36:37], v[34:35], 0, v[36:37]
	global_load_dwordx2 v[230:231], v[36:37], off
	global_load_dwordx2 v[232:233], v[36:37], off offset:32
	global_load_dwordx2 v[234:235], v[36:37], off offset:64
	global_load_dwordx2 v[236:237], v[36:37], off offset:96
	global_load_dwordx2 v[238:239], v[36:37], off offset:128
	global_load_dwordx2 v[240:241], v[36:37], off offset:160
	global_load_dwordx2 v[242:243], v[36:37], off offset:192
	global_load_dwordx2 v[244:245], v[36:37], off offset:224
	v_mbcnt_lo_u32_b32 v250, -1, 0
	v_mbcnt_hi_u32_b32 v250, -1, v250
	v_bfe_u32 v250, v250, 4, 1
	v_mul_u32_u24_e32 v250, 24, v250
	v_mov_b32_e32 v251, 0
	v_lshl_add_u64 v[250:251], v[36:37], 0, v[250:251]
	v_div_fixup_f32 v32, v33, v32, 1.0
	v_pk_mul_f32 v[44:45], v[104:105], v[32:33] op_sel_hi:[1,0]
	v_pk_mul_f32 v[40:41], v[40:41], v[32:33] op_sel_hi:[1,0]
	s_waitcnt vmcnt(7) lgkmcnt(0)
	v_lshlrev_b32_e32 v46, 16, v230
	v_and_b32_e32 v47, 0xffff0000, v230
	v_pk_mul_f32 v[44:45], v[44:45], v[46:47]
	v_lshlrev_b32_e32 v46, 16, v231
	v_cvt_pk_bf16_f32 v246, v44, v45
	v_pk_mul_f32 v[44:45], v[106:107], v[32:33] op_sel_hi:[1,0]
	v_and_b32_e32 v47, 0xffff0000, v231
	v_pk_mul_f32 v[44:45], v[44:45], v[46:47]
	s_nop 0
	v_cvt_pk_bf16_f32 v247, v44, v45
	v_pk_mul_f32 v[44:45], v[96:97], v[32:33] op_sel_hi:[1,0]
	s_waitcnt vmcnt(6) lgkmcnt(0)
	v_lshlrev_b32_e32 v46, 16, v232
	v_and_b32_e32 v47, 0xffff0000, v232
	v_pk_mul_f32 v[44:45], v[44:45], v[46:47]
	v_lshlrev_b32_e32 v46, 16, v233
	v_cvt_pk_bf16_f32 v248, v44, v45
	v_pk_mul_f32 v[44:45], v[98:99], v[32:33] op_sel_hi:[1,0]
	v_and_b32_e32 v47, 0xffff0000, v233
	v_pk_mul_f32 v[44:45], v[44:45], v[46:47]
	s_nop 0
	v_cvt_pk_bf16_f32 v249, v44, v45
	s_nop 1
	v_permlane16_swap_b32_e32 v246, v248
	v_permlane16_swap_b32_e32 v247, v249
	global_store_dwordx4 v[250:251], v[246:249], off
	v_pk_mul_f32 v[44:45], v[92:93], v[32:33] op_sel_hi:[1,0]
	s_waitcnt vmcnt(6) lgkmcnt(0)
	v_lshlrev_b32_e32 v46, 16, v234
	v_and_b32_e32 v47, 0xffff0000, v234
	v_pk_mul_f32 v[44:45], v[44:45], v[46:47]
	v_lshlrev_b32_e32 v46, 16, v235
	v_cvt_pk_bf16_f32 v246, v44, v45
	v_pk_mul_f32 v[44:45], v[94:95], v[32:33] op_sel_hi:[1,0]
	v_and_b32_e32 v47, 0xffff0000, v235
	v_pk_mul_f32 v[44:45], v[44:45], v[46:47]
	s_nop 0
	v_cvt_pk_bf16_f32 v247, v44, v45
	v_pk_mul_f32 v[44:45], v[72:73], v[32:33] op_sel_hi:[1,0]
	s_waitcnt vmcnt(5) lgkmcnt(0)
	v_lshlrev_b32_e32 v46, 16, v236
	v_and_b32_e32 v47, 0xffff0000, v236
	v_pk_mul_f32 v[44:45], v[44:45], v[46:47]
	v_lshlrev_b32_e32 v46, 16, v237
	v_cvt_pk_bf16_f32 v248, v44, v45
	v_pk_mul_f32 v[44:45], v[74:75], v[32:33] op_sel_hi:[1,0]
	v_and_b32_e32 v47, 0xffff0000, v237
	v_pk_mul_f32 v[44:45], v[44:45], v[46:47]
	s_nop 0
	v_cvt_pk_bf16_f32 v249, v44, v45
	s_nop 1
	v_permlane16_swap_b32_e32 v246, v248
	v_permlane16_swap_b32_e32 v247, v249
	global_store_dwordx4 v[250:251], v[246:249], off offset:64
	v_pk_mul_f32 v[44:45], v[64:65], v[32:33] op_sel_hi:[1,0]
	s_waitcnt vmcnt(5) lgkmcnt(0)
	v_lshlrev_b32_e32 v46, 16, v238
	v_and_b32_e32 v47, 0xffff0000, v238
	v_pk_mul_f32 v[44:45], v[44:45], v[46:47]
	v_lshlrev_b32_e32 v46, 16, v239
	v_cvt_pk_bf16_f32 v246, v44, v45
	v_pk_mul_f32 v[44:45], v[66:67], v[32:33] op_sel_hi:[1,0]
	v_and_b32_e32 v47, 0xffff0000, v239
	v_pk_mul_f32 v[44:45], v[44:45], v[46:47]
	s_nop 0
	v_cvt_pk_bf16_f32 v247, v44, v45
	v_pk_mul_f32 v[44:45], v[52:53], v[32:33] op_sel_hi:[1,0]
	s_waitcnt vmcnt(4) lgkmcnt(0)
	v_lshlrev_b32_e32 v46, 16, v240
	v_and_b32_e32 v47, 0xffff0000, v240
	v_pk_mul_f32 v[44:45], v[44:45], v[46:47]
	v_lshlrev_b32_e32 v46, 16, v241
	v_cvt_pk_bf16_f32 v248, v44, v45
	v_pk_mul_f32 v[44:45], v[54:55], v[32:33] op_sel_hi:[1,0]
	v_and_b32_e32 v47, 0xffff0000, v241
	v_pk_mul_f32 v[44:45], v[44:45], v[46:47]
	s_nop 0
	v_cvt_pk_bf16_f32 v249, v44, v45
	s_nop 1
	v_permlane16_swap_b32_e32 v246, v248
	v_permlane16_swap_b32_e32 v247, v249
	global_store_dwordx4 v[250:251], v[246:249], off offset:128
	v_pk_mul_f32 v[44:45], v[48:49], v[32:33] op_sel_hi:[1,0]
	s_waitcnt vmcnt(4) lgkmcnt(0)
	v_lshlrev_b32_e32 v46, 16, v242
	v_and_b32_e32 v47, 0xffff0000, v242
	v_pk_mul_f32 v[44:45], v[44:45], v[46:47]
	v_lshlrev_b32_e32 v46, 16, v243
	v_cvt_pk_bf16_f32 v246, v44, v45
	v_pk_mul_f32 v[44:45], v[50:51], v[32:33] op_sel_hi:[1,0]
	v_and_b32_e32 v47, 0xffff0000, v243
	v_pk_mul_f32 v[44:45], v[44:45], v[46:47]
	v_pk_mul_f32 v[32:33], v[42:43], v[32:33] op_sel_hi:[1,0]
	v_cvt_pk_bf16_f32 v247, v44, v45
	s_waitcnt vmcnt(3) lgkmcnt(0)
; DI float bflo(unsigned v) { return __uint_as_float(v << 16); }
; DI float bfhi(unsigned v) { return __uint_as_float(v & 0xffff0000u); }
; DI int tid_() { int t = threadIdx.x; asm volatile("" : "+v"(t)); return t; }
; DI void attn_c_item(const Params& P, int l, int b, int h, int qb, char* shm, float B2, int dry) {
;     ...
;   for (int qs = 0; qs < 2; ++qs) {
;     float lt = lsum[qs];
;     lt += __shfl_xor(lt, 16);
;     lt += __shfl_xor(lt, 32);
;     const float inv = 1.f / lt;
;     u16* dp = actC + (size_t)(b * SEQ + q0 + qs * 16 + fr) * 512 + h * 128 + fq * 4;
; #pragma unroll
;     for (int dvs = 0; dvs < 8; ++dvs) {
;       u32x2 gz = *(const u32x2*)(dp + dvs * 16);
;       u32x2 ov = {pack2(o[dvs][qs][0] * inv * bflo(gz[0]), o[dvs][qs][1] * inv * bfhi(gz[0])),
;                   pack2(o[dvs][qs][2] * inv * bflo(gz[1]), o[dvs][qs][3] * inv * bfhi(gz[1]))};
;       if (!dry) *(u32x2*)(dp + dvs * 16) = ov;
;     }
;   }
; }
; DI void phase_attn_c(const Params& P, int l, char* shm, int dry) {
;   const int lane = tid_() & 63;
;   float gq = 0.f, gk = 0.f;
; #pragma unroll
;   for (int i = 0; i < 3; ++i) {
;     gq = fmaxf(gq, fabsf(P.q_norm_g[l * 192 + lane + i * 64]));
;     gk = fmaxf(gk, fabsf(P.k_norm_g[l * 192 + lane + i * 64]));
;   }
; #pragma unroll
;   for (int o = 32; o > 0; o >>= 1) { gq = fmaxf(gq, __shfl_xor(gq, o)); gk = fmaxf(gk, __shfl_xor(gk, o)); }
;   const float B2 = 13.856406460551018f * 1.4426950408889634f * gq * gk;
;   for (int it = blockIdx.x; it < 256; it += gridDim.x) {
;     const int bh = it >> 4, pr = it & 15, b = bh >> 2, h = bh & 3;
; #pragma clang loop unroll(disable)
;     for (int hf = 0; hf < 2; ++hf) attn_c_item(P, l, b, h, hf ? pr : 31 - pr, shm, B2, dry);
	v_lshlrev_b32_e32 v44, 16, v244
	v_and_b32_e32 v45, 0xffff0000, v244
	v_pk_mul_f32 v[40:41], v[40:41], v[44:45]
	s_nop 0
	v_cvt_pk_bf16_f32 v248, v40, v41
	v_lshlrev_b32_e32 v40, 16, v245
	v_and_b32_e32 v41, 0xffff0000, v245
	v_pk_mul_f32 v[32:33], v[32:33], v[40:41]
	s_nop 0
	v_cvt_pk_bf16_f32 v249, v32, v33
	ds_bpermute_b32 v32, v212, v118
	s_nop 1
	v_permlane16_swap_b32_e32 v246, v248
	v_permlane16_swap_b32_e32 v247, v249
	global_store_dwordx4 v[250:251], v[246:249], off offset:192
	s_waitcnt lgkmcnt(0)
	v_add_f32_e32 v32, v118, v32
	ds_bpermute_b32 v33, v211, v32
	s_waitcnt lgkmcnt(0)
	v_add_f32_e32 v32, v32, v33
	v_div_scale_f32 v33, s[0:1], v32, v32, 1.0
	v_rcp_f32_e32 v36, v33
	s_mov_b64 s[0:1], 0
	v_fma_f32 v37, -v33, v36, 1.0
	v_fmac_f32_e32 v36, v37, v36
	v_div_scale_f32 v37, vcc, 1.0, v32, 1.0
	v_mul_f32_e32 v38, v37, v36
	v_fma_f32 v39, -v33, v38, v37
	v_fmac_f32_e32 v38, v39, v36
	v_fma_f32 v33, -v33, v38, v37
	v_div_fmas_f32 v33, v33, v36, v38
	v_lshlrev_b64 v[36:37], 10, v[112:113]
	v_lshl_add_u64 v[34:35], v[34:35], 0, v[36:37]
	global_load_dwordx2 v[230:231], v[34:35], off
	global_load_dwordx2 v[232:233], v[34:35], off offset:32
	global_load_dwordx2 v[234:235], v[34:35], off offset:64
	global_load_dwordx2 v[236:237], v[34:35], off offset:96
	global_load_dwordx2 v[238:239], v[34:35], off offset:128
	global_load_dwordx2 v[240:241], v[34:35], off offset:160
	global_load_dwordx2 v[242:243], v[34:35], off offset:192
	global_load_dwordx2 v[244:245], v[34:35], off offset:224
	v_mbcnt_lo_u32_b32 v250, -1, 0
	v_mbcnt_hi_u32_b32 v250, -1, v250
	v_bfe_u32 v250, v250, 4, 1
	v_mul_u32_u24_e32 v250, 24, v250
	v_mov_b32_e32 v251, 0
	v_lshl_add_u64 v[250:251], v[34:35], 0, v[250:251]
	v_div_fixup_f32 v32, v33, v32, 1.0
	v_pk_mul_f32 v[28:29], v[28:29], v[32:33] op_sel_hi:[1,0]
	v_pk_mul_f32 v[30:31], v[30:31], v[32:33] op_sel_hi:[1,0]
	v_pk_mul_f32 v[24:25], v[24:25], v[32:33] op_sel_hi:[1,0]
	v_pk_mul_f32 v[26:27], v[26:27], v[32:33] op_sel_hi:[1,0]
	v_pk_mul_f32 v[20:21], v[20:21], v[32:33] op_sel_hi:[1,0]
	v_pk_mul_f32 v[22:23], v[22:23], v[32:33] op_sel_hi:[1,0]
	v_pk_mul_f32 v[16:17], v[16:17], v[32:33] op_sel_hi:[1,0]
	v_pk_mul_f32 v[18:19], v[18:19], v[32:33] op_sel_hi:[1,0]
	v_pk_mul_f32 v[12:13], v[12:13], v[32:33] op_sel_hi:[1,0]
	v_pk_mul_f32 v[14:15], v[14:15], v[32:33] op_sel_hi:[1,0]
	v_pk_mul_f32 v[8:9], v[8:9], v[32:33] op_sel_hi:[1,0]
	v_pk_mul_f32 v[10:11], v[10:11], v[32:33] op_sel_hi:[1,0]
	v_pk_mul_f32 v[4:5], v[4:5], v[32:33] op_sel_hi:[1,0]
	v_pk_mul_f32 v[6:7], v[6:7], v[32:33] op_sel_hi:[1,0]
	v_pk_mul_f32 v[0:1], v[0:1], v[32:33] op_sel_hi:[1,0]
	v_pk_mul_f32 v[2:3], v[2:3], v[32:33] op_sel_hi:[1,0]
	s_and_b64 vcc, exec, s[20:21]
	s_waitcnt vmcnt(7) lgkmcnt(0)
	v_lshlrev_b32_e32 v38, 16, v230
	v_and_b32_e32 v39, 0xffff0000, v230
	v_lshlrev_b32_e32 v36, 16, v231
	v_and_b32_e32 v37, 0xffff0000, v231
	v_pk_mul_f32 v[28:29], v[28:29], v[38:39]
	v_pk_mul_f32 v[30:31], v[30:31], v[36:37]
	v_cvt_pk_bf16_f32 v246, v28, v29
	v_cvt_pk_bf16_f32 v247, v30, v31
	s_waitcnt vmcnt(6) lgkmcnt(0)
	v_lshlrev_b32_e32 v30, 16, v232
	v_and_b32_e32 v31, 0xffff0000, v232
	v_lshlrev_b32_e32 v28, 16, v233
	v_and_b32_e32 v29, 0xffff0000, v233
	v_pk_mul_f32 v[24:25], v[24:25], v[30:31]
	v_pk_mul_f32 v[26:27], v[26:27], v[28:29]
	v_cvt_pk_bf16_f32 v248, v24, v25
	v_cvt_pk_bf16_f32 v249, v26, v27
	s_nop 1
	v_permlane16_swap_b32_e32 v246, v248
	v_permlane16_swap_b32_e32 v247, v249
	global_store_dwordx4 v[250:251], v[246:249], off
	s_waitcnt vmcnt(6) lgkmcnt(0)
	v_lshlrev_b32_e32 v26, 16, v234
	v_and_b32_e32 v27, 0xffff0000, v234
	v_lshlrev_b32_e32 v24, 16, v235
	v_and_b32_e32 v25, 0xffff0000, v235
	v_pk_mul_f32 v[20:21], v[20:21], v[26:27]
	v_pk_mul_f32 v[22:23], v[22:23], v[24:25]
	v_cvt_pk_bf16_f32 v246, v20, v21
	v_cvt_pk_bf16_f32 v247, v22, v23
	s_waitcnt vmcnt(5) lgkmcnt(0)
	v_lshlrev_b32_e32 v22, 16, v236
	v_and_b32_e32 v23, 0xffff0000, v236
	v_lshlrev_b32_e32 v20, 16, v237
	v_and_b32_e32 v21, 0xffff0000, v237
	v_pk_mul_f32 v[16:17], v[16:17], v[22:23]
	v_pk_mul_f32 v[18:19], v[18:19], v[20:21]
	v_cvt_pk_bf16_f32 v248, v16, v17
	v_cvt_pk_bf16_f32 v249, v18, v19
	s_nop 1
	v_permlane16_swap_b32_e32 v246, v248
	v_permlane16_swap_b32_e32 v247, v249
	global_store_dwordx4 v[250:251], v[246:249], off offset:64
	s_waitcnt vmcnt(5) lgkmcnt(0)
	v_lshlrev_b32_e32 v18, 16, v238
	v_and_b32_e32 v19, 0xffff0000, v238
	v_lshlrev_b32_e32 v16, 16, v239
	v_and_b32_e32 v17, 0xffff0000, v239
	v_pk_mul_f32 v[12:13], v[12:13], v[18:19]
	v_pk_mul_f32 v[14:15], v[14:15], v[16:17]
	v_cvt_pk_bf16_f32 v246, v12, v13
	v_cvt_pk_bf16_f32 v247, v14, v15
	s_waitcnt vmcnt(4) lgkmcnt(0)
	v_lshlrev_b32_e32 v14, 16, v240
	v_and_b32_e32 v15, 0xffff0000, v240
	v_lshlrev_b32_e32 v12, 16, v241
	v_and_b32_e32 v13, 0xffff0000, v241
	v_pk_mul_f32 v[8:9], v[8:9], v[14:15]
	v_pk_mul_f32 v[10:11], v[10:11], v[12:13]
	v_cvt_pk_bf16_f32 v248, v8, v9
	v_cvt_pk_bf16_f32 v249, v10, v11
	s_nop 1
	v_permlane16_swap_b32_e32 v246, v248
	v_permlane16_swap_b32_e32 v247, v249
	global_store_dwordx4 v[250:251], v[246:249], off offset:128
	s_waitcnt vmcnt(4) lgkmcnt(0)
	v_lshlrev_b32_e32 v10, 16, v242
	v_and_b32_e32 v11, 0xffff0000, v242
	v_lshlrev_b32_e32 v8, 16, v243
	v_and_b32_e32 v9, 0xffff0000, v243
	v_pk_mul_f32 v[4:5], v[4:5], v[10:11]
	v_pk_mul_f32 v[6:7], v[6:7], v[8:9]
	v_cvt_pk_bf16_f32 v246, v4, v5
	v_cvt_pk_bf16_f32 v247, v6, v7
	s_waitcnt vmcnt(3) lgkmcnt(0)
	v_lshlrev_b32_e32 v6, 16, v244
	v_and_b32_e32 v7, 0xffff0000, v244
	v_lshlrev_b32_e32 v4, 16, v245
	v_and_b32_e32 v5, 0xffff0000, v245
	v_pk_mul_f32 v[0:1], v[0:1], v[6:7]
	v_pk_mul_f32 v[2:3], v[2:3], v[4:5]
	v_cvt_pk_bf16_f32 v248, v0, v1
	v_cvt_pk_bf16_f32 v249, v2, v3
	s_nop 1
	v_permlane16_swap_b32_e32 v246, v248
	v_permlane16_swap_b32_e32 v247, v249
	global_store_dwordx4 v[250:251], v[246:249], off offset:192
	s_cbranch_vccz .LBB0_575
	s_add_i32 s28, s28, s72
	s_cmpk_gt_i32 s28, 0xff
	s_cbranch_scc0 .LBB0_574
	v_readlane_b32 s50, v252, 18
	v_readlane_b32 s51, v252, 19
	s_movk_i32 s42, 0xfc0
	v_readlane_b32 s46, v252, 31
	s_mov_b64 s[34:35], 0x20000
	s_mov_b64 s[36:37], 0x8000
	s_mov_b64 s[38:39], 0x18000

; template <int MF, int NF, bool SWAP = true>
; DI void gemm_main(f32x4 (&acc)[MF][NF], const u16* __restrict__ Ab, int lda, const u16* __restrict__ Bb, int ldb,
;                   int K, char* shm) {
;     ...
;   int sR0, sC0;
;   stage_rc<2>(wid * 1024 + lane * 16, sR0, sC0);
; #pragma unroll
;   for (int m = 0; m < MF; ++m)
; #pragma unroll
;     for (int n = 0; n < NF; ++n) acc[m][n] = f32x4{0.f, 0.f, 0.f, 0.f};
;   const int nt = K >> 6;
;   const int pa0 = sR0 * lda + sC0, pb0 = sR0 * ldb + sC0;
;     ...
;   const int a_off = lds_byte<2>(fr, fq * 8) + wr * (MF * 2048);
;   const int b_off = lds_byte<2>(fr, fq * 8) + wc * (NF * 2048);
;   G_STAGE(0, 0);
;   if constexpr (RING3) {
;     if (nt > 1) { G_STAGE(1, 1); asm volatile("s_waitcnt vmcnt(6)" ::: "memory"); }
;     else asm volatile("s_waitcnt vmcnt(0)" ::: "memory");
;     asm volatile("s_waitcnt lgkmcnt(0)" ::: "memory");
;     __builtin_amdgcn_s_barrier();
;   } else {
;     asm volatile("s_waitcnt vmcnt(0)" ::: "memory");
;     __syncthreads();
;   }
.LBB0_587:
	s_ashr_i32 s0, s20, 31
	s_lshr_b32 s0, s0, 29
	s_add_i32 s0, s20, s0
	s_ashr_i32 s1, s0, 3
	s_and_b32 s0, s0, -8
	s_sub_i32 s0, s20, s0
	s_lshr_b32 s4, s0, 31
	s_or_b32 s4, s4, 0x60
	s_mul_i32 s0, s4, s0
	s_add_i32 s0, s0, s1
	s_mul_hi_i32 s1, s0, 0x2aaaaaab
	s_lshr_b32 s4, s1, 31
	s_ashr_i32 s1, s1, 3
	s_add_i32 s1, s1, s4
	s_lshl_b32 s4, s1, 3
	s_sub_i32 s5, 0x80, s4
	s_min_u32 s5, s5, 8
	s_mul_i32 s1, s1, 48
	s_sub_i32 s12, s0, s1
	v_cvt_f32_ubyte0_e32 v1, s5
	v_cvt_f32_i32_e32 v0, s12
	v_rcp_iflag_f32_e32 v2, v1
	s_ashr_i32 s0, s12, 30
	s_or_b32 s13, s0, 1
	v_mov_b32_e32 v10, v135
	v_mul_f32_e32 v2, v0, v2
	v_trunc_f32_e32 v2, v2
	v_fma_f32 v0, -v2, v1, v0
	v_cvt_i32_f32_e32 v2, v2
	v_cmp_ge_f32_e64 s[0:1], |v0|, v1
	s_and_b64 s[0:1], s[0:1], exec
	s_cselect_b32 s0, s13, 0
	v_readfirstlane_b32 s1, v2
	s_add_i32 s0, s1, s0
	s_lshl_b32 s17, s0, 24
	s_sext_i32_i8 s1, s0
	s_mul_i32 s0, s0, s5
	s_sub_i32 s0, s12, s0
	v_lshlrev_b32_e32 v0, 4, v10
	v_and_b32_e32 v2, 32, v10
	v_ashrrev_i32_e32 v11, 6, v10
	v_lshrrev_b32_e32 v3, 31, v10
	v_bitop3_b32 v0, v0, v2, 48 bitop3:0x6c
	s_sext_i32_i8 s0, s0
	v_add_u32_e32 v3, v11, v3
	v_lshrrev_b32_e32 v13, 1, v0
	v_lshlrev_b32_e32 v0, 8, v10
	s_add_i32 s4, s4, s0
	v_and_b32_e32 v1, 15, v10
	v_ashrrev_i32_e32 v12, 1, v3
	v_and_b32_e32 v3, 0x7fffffe, v3
	v_and_b32_e32 v14, 0x3c00, v0
	s_lshl_b32 s12, s4, 8
	v_sub_u32_e32 v3, v11, v3
	v_lshl_or_b32 v0, v12, 14, v14
	v_lshlrev_b32_e32 v15, 6, v1
	v_lshlrev_b32_e32 v1, 2, v10
	s_ashr_i32 s13, s12, 31
	v_lshl_add_u32 v0, v3, 5, v0
	v_and_b32_e32 v16, 32, v1
	v_lshlrev_b32_e32 v1, 6, v10
	s_lshl_b32 s14, s1, 8
	s_lshl_b64 s[0:1], s[12:13], 11
	v_or_b32_e32 v0, v0, v13
	v_and_b32_e32 v129, 0xffffc000, v1
	v_lshlrev_b32_e32 v1, 13, v11
	s_add_u32 s0, s18, s0
	v_lshlrev_b32_e32 v128, 10, v11
	v_and_b32_e32 v131, 0x6000, v1
	v_ashrrev_i32_e32 v1, 31, v0
	s_addc_u32 s1, s19, s1
	v_lshlrev_b64 v[2:3], 1, v[0:1]
	v_readfirstlane_b32 s13, v128
	v_lshl_add_u64 v[4:5], s[0:1], 0, v[2:3]
	s_mov_b32 m0, s13
	v_add_u32_e32 v1, 0x2000, v128
	v_add_u32_e32 v0, 0x20000, v0
	global_load_lds_dwordx4 v[4:5], off
	v_lshl_add_u64 v[4:5], v[2:3], 0, s[34:35]
	v_readfirstlane_b32 s13, v1
	v_ashrrev_i32_e32 v1, 31, v0
	v_add_u32_e32 v8, 0x4000, v128
	v_lshl_add_u64 v[6:7], s[0:1], 0, v[4:5]
	s_mov_b32 m0, s13
	v_lshlrev_b64 v[0:1], 1, v[0:1]
	v_readfirstlane_b32 s13, v8
	global_load_lds_dwordx4 v[6:7], off
	v_lshl_add_u64 v[6:7], s[0:1], 0, v[0:1]
	s_mov_b32 m0, s13
	v_add_u32_e32 v17, 0x6000, v128
	global_load_lds_dwordx4 v[6:7], off
	v_lshl_add_u64 v[6:7], v[2:3], 0, s[86:87]
	v_readfirstlane_b32 s13, v17
	s_ashr_i32 s15, s14, 31
	v_lshl_add_u64 v[8:9], s[0:1], 0, v[6:7]
	s_mov_b32 m0, s13
	s_lshl_b64 s[4:5], s[14:15], 11
	global_load_lds_dwordx4 v[8:9], off
	v_and_b32_e32 v8, 48, v10
	s_add_u32 s4, s8, s4
	v_bitop3_b32 v132, v15, v16, v8 bitop3:0x36
	v_add_u32_e32 v8, 0x8000, v128
	s_addc_u32 s5, s9, s5
	v_readfirstlane_b32 s13, v8
	v_lshl_add_u64 v[2:3], s[4:5], 0, v[2:3]
	s_mov_b32 m0, s13
	v_lshl_add_u64 v[0:1], s[4:5], 0, v[0:1]
	global_load_lds_dwordx4 v[2:3], off
	v_lshl_add_u64 v[2:3], s[4:5], 0, v[4:5]
	v_add_u32_e32 v4, 0xa000, v128
	s_mov_b32 s16, 0
	v_readfirstlane_b32 s13, v4
	s_mov_b32 m0, s13
	s_mov_b32 s15, 0
	global_load_lds_dwordx4 v[2:3], off
	v_add_u32_e32 v2, 0xc000, v128
	s_nop 0
	v_readfirstlane_b32 s13, v2
	v_add_u32_e32 v2, 0xe000, v128
	s_mov_b32 m0, s13
	v_readfirstlane_b32 s13, v2
	global_load_lds_dwordx4 v[0:1], off
	v_lshl_add_u64 v[0:1], s[4:5], 0, v[6:7]
	s_mov_b32 m0, s13
	s_mov_b32 s13, 0
	global_load_lds_dwordx4 v[0:1], off
	v_mul_lo_u32 v0, v12, s70
	s_waitcnt vmcnt(0)
	v_or_b32_e32 v0, v13, v0
	v_lshlrev_b32_e32 v1, 5, v11
	v_add3_u32 v136, v0, v14, v1
	v_mov_b32_e32 v0, 0
	v_mov_b32_e32 v1, v0
	v_mov_b32_e32 v2, v0
	v_mov_b32_e32 v3, v0
	v_mov_b32_e32 v4, v0
	v_mov_b32_e32 v5, v0
	v_mov_b32_e32 v6, v0
	v_mov_b32_e32 v7, v0
	v_mov_b32_e32 v8, v0
	v_mov_b32_e32 v9, v0
	v_mov_b32_e32 v10, v0
	v_mov_b32_e32 v11, v0
	v_mov_b32_e32 v12, v0
	v_mov_b32_e32 v13, v0
	v_mov_b32_e32 v14, v0
	v_mov_b32_e32 v15, v0
	v_mov_b32_e32 v16, v0
	v_mov_b32_e32 v17, v0
	v_mov_b32_e32 v18, v0
	v_mov_b32_e32 v19, v0
	v_mov_b32_e32 v20, v0
	v_mov_b32_e32 v21, v0
	v_mov_b32_e32 v22, v0
	v_mov_b32_e32 v23, v0
	v_mov_b32_e32 v24, v0
	v_mov_b32_e32 v25, v0
	v_mov_b32_e32 v26, v0
	v_mov_b32_e32 v27, v0
	v_mov_b32_e32 v28, v0
	v_mov_b32_e32 v29, v0
	v_mov_b32_e32 v30, v0
	v_mov_b32_e32 v31, v0
	v_mov_b32_e32 v32, v0
	v_mov_b32_e32 v33, v0
	v_mov_b32_e32 v34, v0
	v_mov_b32_e32 v35, v0
	v_mov_b32_e32 v36, v0
	v_mov_b32_e32 v37, v0
	v_mov_b32_e32 v38, v0
	v_mov_b32_e32 v39, v0
	v_mov_b32_e32 v40, v0
	v_mov_b32_e32 v41, v0
	v_mov_b32_e32 v42, v0
	v_mov_b32_e32 v43, v0
	v_mov_b32_e32 v44, v0
	v_mov_b32_e32 v45, v0
	v_mov_b32_e32 v46, v0
	v_mov_b32_e32 v47, v0
	v_mov_b32_e32 v48, v0
	v_mov_b32_e32 v49, v0
	v_mov_b32_e32 v50, v0
	v_mov_b32_e32 v51, v0
	v_mov_b32_e32 v52, v0
	v_mov_b32_e32 v53, v0
	v_mov_b32_e32 v54, v0
	v_mov_b32_e32 v55, v0
	v_mov_b32_e32 v56, v0
	v_mov_b32_e32 v57, v0
	v_mov_b32_e32 v58, v0
	v_mov_b32_e32 v59, v0
	v_mov_b32_e32 v60, v0
	v_mov_b32_e32 v61, v0
	v_mov_b32_e32 v62, v0
	v_mov_b32_e32 v63, v0
	v_mov_b32_e32 v64, v0
	v_mov_b32_e32 v65, v0
	v_mov_b32_e32 v66, v0
	v_mov_b32_e32 v67, v0
	v_mov_b32_e32 v68, v0
	v_mov_b32_e32 v69, v0
	v_mov_b32_e32 v70, v0
	v_mov_b32_e32 v71, v0
	v_mov_b32_e32 v72, v0
	v_mov_b32_e32 v73, v0
	v_mov_b32_e32 v74, v0
	v_mov_b32_e32 v75, v0
	v_mov_b32_e32 v76, v0
	v_mov_b32_e32 v77, v0
	v_mov_b32_e32 v78, v0
	v_mov_b32_e32 v79, v0
	v_mov_b32_e32 v80, v0
	v_mov_b32_e32 v81, v0
	v_mov_b32_e32 v82, v0
	v_mov_b32_e32 v83, v0
	v_mov_b32_e32 v84, v0
	v_mov_b32_e32 v85, v0
	v_mov_b32_e32 v86, v0
	v_mov_b32_e32 v87, v0
	v_mov_b32_e32 v88, v0
	v_mov_b32_e32 v89, v0
	v_mov_b32_e32 v90, v0
	v_mov_b32_e32 v91, v0
	v_mov_b32_e32 v92, v0
	v_mov_b32_e32 v93, v0
	v_mov_b32_e32 v94, v0
	v_mov_b32_e32 v95, v0
	v_mov_b32_e32 v96, v0
	v_mov_b32_e32 v97, v0
	v_mov_b32_e32 v98, v0
	v_mov_b32_e32 v99, v0
	v_mov_b32_e32 v100, v0
	v_mov_b32_e32 v101, v0
	v_mov_b32_e32 v102, v0
	v_mov_b32_e32 v103, v0
	v_mov_b32_e32 v104, v0
	v_mov_b32_e32 v105, v0
	v_mov_b32_e32 v106, v0
	v_mov_b32_e32 v107, v0
	v_mov_b32_e32 v108, v0
	v_mov_b32_e32 v109, v0
	v_mov_b32_e32 v110, v0
	v_mov_b32_e32 v111, v0
	v_mov_b32_e32 v112, v0
	v_mov_b32_e32 v113, v0
	v_mov_b32_e32 v114, v0
	v_mov_b32_e32 v115, v0
	v_mov_b32_e32 v116, v0
	v_mov_b32_e32 v117, v0
	v_mov_b32_e32 v118, v0
	v_mov_b32_e32 v119, v0
	v_mov_b32_e32 v120, v0
	v_mov_b32_e32 v121, v0
	v_mov_b32_e32 v122, v0
	v_mov_b32_e32 v123, v0
	v_mov_b32_e32 v124, v0
	v_mov_b32_e32 v125, v0
	v_mov_b32_e32 v126, v0
	v_mov_b32_e32 v127, v0
	s_waitcnt vmcnt(0) lgkmcnt(0)
	s_barrier
	s_nop 0
	s_nop 0
	s_branch .LBB0_589
